# GU: next-tile index computation moved from the exposed unit head into the peeled second load segment (runs under the partner's MFMA block)
# baseline (speedup 1.0000x reference)
; #define PG8_STAGE(bufoff, gbase, voff) do { _Pragma("unroll") for (int _i = 0; _i < 2; ++_i) \
;         __builtin_amdgcn_global_load_lds((const unsigned*)((const char*)(gbase) + (voff)[_i]), (PG8_LAS unsigned*)(lds + (bufoff) + ldsw + _i * 8192), 16, 0, 0); } while (0)
; #define PG8_LDA(dst, b, h) do { _Pragma("unroll") for (int m = 0; m < 4; ++m) _Pragma("unroll") for (int k = 0; k < 2; ++k) dst[m][k] = *(const PG8_LAS bf16x8*)(lds + PG8_SA(b, h) + aoff + m * 2048 + k * 1024); } while (0)
;     __host__ __device__ bool next(int i, Unit& u) const {
;         if (rev) { const int nr = nwg / G; if (i >= nr) return false; i = nr - 1 - i; }
;         const long L = (long)i * G + c; if (L >= nwg) return false;
;         int wgid = (int)L; { const int q = nwg / NXCD, r = nwg % NXCD, xcd = wgid % NXCD, off = wgid / NXCD; wgid = (xcd < r ? xcd * (q + 1) : r * (q + 1) + (xcd - r) * q) + off; }
;         const int nig = WGM * nN, gid = wgid / nig, fm = gid * WGM, gsz = (nM - fm) < WGM ? (nM - fm) : WGM;
;         u.pm = fm + ((wgid % nig) % gsz); u.pn = (wgid % nig) / gsz; return true;
;     }
; template <class Epi, class Sched, bool ALIGN_EPI = false, bool SP2 = true>
; __device__ __forceinline__ void gemm_phase(PG8_LAS unsigned char* lds, const Gemm g, const Sched& S, const Epi& E) {
;     ...
;         const bool has_next = S.next(ui + 1, nxt);
;         const char* nA = has_next ? (const char*)g.A + (size_t)nxt.pm * tstepA + (size_t)nxt.pn * pnA : cA; const char* nB = has_next ? (const char*)g.Bt + (size_t)nxt.pn * tstep : cB;
;         for (int t = 0; t < nt; t += 2) {
;             const bool last = (t == nt - 2);
;             const char* a1 = cA + (size_t)(t + 1) * kstepA;
;             const char* a2 = last ? nA : cA + (size_t)(t + 2) * kstepA; const char* b2 = last ? nB : cB + (size_t)(t + 2) * kstep;
;             const char* a3 = a2 + kstepA; const char* b3 = b2 + kstep;
;             if (last && has_next) S.a_ready(nxt);
;             if constexpr (SP2) {
;             PG8_LDB(B0, 0, 0); PG8_LDB(B1, 0, 1); PG8_SCHED; PG8_LDA(At, 0, 0); PG8_STAGE(PG8_SA(1, 1), a1 + hstepA, voffA);
;             PG8_WAIT_V(8); PG8_WAIT_L(0); PG8_BAR; PG8_MMA(0, 0, At, B0); PG8_MMA(0, 1, At, B1); PG8_BAR; PG8_SCHED;
;             PG8_LDA(At, 0, 1); PG8_STAGE(PG8_SB(0, 0), b2, voffB); PG8_STAGE(PG8_SB(0, 1), b2 + hstep, voffB); PG8_STAGE(PG8_SA(0, 0), a2, voffA);
.LBB0_125:
	s_add_i32 s57, s57, 1
	s_mov_b64 s[98:99], s[46:47]
	s_add_u32 s46, s46, 0x40080
	s_addc_u32 s47, s47, 0
	s_add_u32 s6, s48, 0x100
	s_addc_u32 s7, s49, 0
	s_mov_b32 s60, -2
	s_waitcnt lgkmcnt(0)
	s_add_u32 s14, s46, 0xfffc0080
	s_addc_u32 s15, s47, -1
	s_add_i32 s70, 0, 0x10000
	s_cmp_eq_u32 s60, 12
	s_cselect_b32 s51, s17, s15
	s_cselect_b32 s50, s39, s14
	v_add_u32_e32 v141, s70, v147
	s_cselect_b32 s49, s25, s7
	s_cselect_b32 s48, s59, s6
	s_add_i32 s71, 0, 0x14000
	ds_read_b128 v[152:155], v141
	ds_read_b128 v[156:159], v141 offset:1024
	ds_read_b128 v[160:163], v141 offset:2048
	ds_read_b128 v[164:167], v141 offset:3072
	s_cmp_lg_u32 s57, 1
	s_cbranch_scc1 .Lgu_s1_nofirst
	v_add_u32_e32 v141, s71, v147
	ds_read_b128 v[168:171], v141
	ds_read_b128 v[172:175], v141 offset:1024
	ds_read_b128 v[176:179], v141 offset:2048
	ds_read_b128 v[180:183], v141 offset:3072
	ds_read_b128 v[184:187], v150
	ds_read_b128 v[188:191], v150 offset:1024
	ds_read_b128 v[200:203], v150 offset:2048
	ds_read_b128 v[204:207], v150 offset:3072
	ds_read_b128 v[208:211], v150 offset:4096
	ds_read_b128 v[212:215], v150 offset:5120
	ds_read_b128 v[216:219], v150 offset:6144
	ds_read_b128 v[220:223], v150 offset:7168
.Lgu_s1_nofirst:
	v_lshl_add_u64 v[148:149], s[46:47], 0, v[136:137]
	s_add_i32 m0, s29, 0xc000
	s_nop 0
	global_load_lds_dwordx4 v[148:149], off
	v_lshl_add_u64 v[148:149], s[46:47], 0, v[138:139]
	s_add_i32 m0, s29, 0xe000
	s_nop 0
	global_load_lds_dwordx4 v[148:149], off
	s_waitcnt vmcnt(12)
	s_waitcnt lgkmcnt(0)
	s_setprio 1
	s_barrier
	v_mfma_f32_16x16x32_bf16 v[120:123], v[152:155], v[184:187], 0
	v_mfma_f32_16x16x32_bf16 v[112:115], v[160:163], v[184:187], 0
	v_mfma_f32_16x16x32_bf16 v[108:111], v[152:155], v[200:203], 0
	v_mfma_f32_16x16x32_bf16 v[96:99], v[160:163], v[200:203], 0
	v_mfma_f32_16x16x32_bf16 v[92:95], v[152:155], v[208:211], 0
	v_mfma_f32_16x16x32_bf16 v[80:83], v[160:163], v[208:211], 0
	v_mfma_f32_16x16x32_bf16 v[76:79], v[152:155], v[216:219], 0
	v_mfma_f32_16x16x32_bf16 v[64:67], v[160:163], v[216:219], 0
	v_mfma_f32_16x16x32_bf16 v[120:123], v[156:159], v[188:191], v[120:123]
	v_mfma_f32_16x16x32_bf16 v[112:115], v[164:167], v[188:191], v[112:115]
	v_mfma_f32_16x16x32_bf16 v[108:111], v[156:159], v[204:207], v[108:111]
	v_mfma_f32_16x16x32_bf16 v[96:99], v[164:167], v[204:207], v[96:99]
	v_mfma_f32_16x16x32_bf16 v[92:95], v[156:159], v[212:215], v[92:95]
	v_mfma_f32_16x16x32_bf16 v[80:83], v[164:167], v[212:215], v[80:83]
	v_mfma_f32_16x16x32_bf16 v[76:79], v[156:159], v[220:223], v[76:79]
	v_mfma_f32_16x16x32_bf16 v[64:67], v[164:167], v[220:223], v[64:67]
	v_mfma_f32_16x16x32_bf16 v[124:127], v[168:171], v[184:187], 0
	v_mfma_f32_16x16x32_bf16 v[116:119], v[176:179], v[184:187], 0
	v_mfma_f32_16x16x32_bf16 v[104:107], v[168:171], v[200:203], 0
	v_mfma_f32_16x16x32_bf16 v[100:103], v[176:179], v[200:203], 0
	v_mfma_f32_16x16x32_bf16 v[88:91], v[168:171], v[208:211], 0
	v_mfma_f32_16x16x32_bf16 v[84:87], v[176:179], v[208:211], 0
	v_mfma_f32_16x16x32_bf16 v[72:75], v[168:171], v[216:219], 0
	v_mfma_f32_16x16x32_bf16 v[68:71], v[176:179], v[216:219], 0
	v_mfma_f32_16x16x32_bf16 v[124:127], v[172:175], v[188:191], v[124:127]
	v_mfma_f32_16x16x32_bf16 v[116:119], v[180:183], v[188:191], v[116:119]
	v_mfma_f32_16x16x32_bf16 v[104:107], v[172:175], v[204:207], v[104:107]
	v_mfma_f32_16x16x32_bf16 v[100:103], v[180:183], v[204:207], v[100:103]
	v_mfma_f32_16x16x32_bf16 v[88:91], v[172:175], v[212:215], v[88:91]
	v_mfma_f32_16x16x32_bf16 v[84:87], v[180:183], v[212:215], v[84:87]
	v_mfma_f32_16x16x32_bf16 v[72:75], v[172:175], v[220:223], v[72:75]
	v_mfma_f32_16x16x32_bf16 v[68:71], v[180:183], v[220:223], v[68:71]
	s_setprio 0
	s_barrier
	s_add_i32 s14, s70, s28
	v_lshl_add_u64 v[148:149], s[48:49], 0, v[132:133]
	s_mov_b32 m0, s14
	ds_read_b128 v[184:187], v150 offset:16384
	ds_read_b128 v[188:191], v150 offset:17408
	ds_read_b128 v[200:203], v150 offset:18432
	ds_read_b128 v[204:207], v150 offset:19456
	ds_read_b128 v[208:211], v150 offset:20480
	ds_read_b128 v[212:215], v150 offset:21504
	ds_read_b128 v[216:219], v150 offset:22528
	ds_read_b128 v[220:223], v150 offset:23552
	global_load_lds_dwordx4 v[148:149], off
	s_add_i32 m0, s14, 0x2000
	v_lshl_add_u64 v[224:225], s[48:49], 0, v[128:129]
	global_load_lds_dwordx4 v[224:225], off
	v_lshl_add_u64 v[234:235], s[50:51], 0, v[130:131]
	v_lshl_add_u64 v[226:227], s[50:51], 0, v[134:135]
	s_mov_b32 m0, s29
	s_nop 0
	global_load_lds_dwordx4 v[226:227], off
	s_mov_b32 m0, s30
	s_nop 0
	global_load_lds_dwordx4 v[234:235], off
	s_mul_i32 s100, s57, s3
	s_mul_hi_u32 s101, s57, s90
	s_add_i32 s101, s101, s100
	s_mul_i32 s100, s57, s90
	s_add_u32 s40, s100, s2
	s_addc_u32 s41, s101, s33
	v_mov_b64_e32 v[0:1], 0xb00
	v_cmp_lt_i64_e64 s[36:37], s[40:41], v[0:1]
	v_mov_b64_e32 v[0:1], 0xaff
	v_cmp_gt_i64_e32 vcc, s[40:41], v[0:1]
	s_cbranch_vccnz .Lgu_idx_skip
	s_ashr_i32 s100, s40, 31
	s_lshr_b32 s100, s100, 29
	s_add_i32 s100, s40, s100
	s_ashr_i32 s101, s100, 3
	s_and_b32 s100, s100, -8
	s_sub_i32 s100, s40, s100
	s_cmp_lt_i32 s100, 0
	s_cselect_b32 s14, s4, 0x160
	s_mul_i32 s100, s100, s14
	s_add_i32 s100, s100, s101
	s_mul_hi_i32 s101, s100, 0x2e8ba2e9
	s_lshr_b32 s14, s101, 31
	s_ashr_i32 s101, s101, 5
	s_add_i32 s101, s101, s14
	s_lshl_b32 s14, s101, 3
	s_sub_i32 s15, 0x80, s14
	s_min_i32 s15, s15, 8
	s_abs_i32 s17, s15
	v_cvt_f32_u32_e32 v0, s17
	s_sub_i32 s25, 0, s17
	s_mulk_i32 s101, 0xb0
	s_sub_i32 s100, s100, s101
	v_rcp_iflag_f32_e32 v0, v0
	s_abs_i32 s101, s100
	s_xor_b32 s24, s100, s15
	s_ashr_i32 s24, s24, 31
	v_mul_f32_e32 v0, 0x4f7ffffe, v0
	v_cvt_u32_f32_e32 v0, v0
	s_nop 0
	v_readfirstlane_b32 s38, v0
	s_mul_i32 s25, s25, s38
	s_mul_hi_u32 s25, s38, s25
	s_add_i32 s38, s38, s25
	s_mul_hi_u32 s25, s101, s38
	s_mul_i32 s38, s25, s17
	s_sub_i32 s101, s101, s38
	s_add_i32 s39, s25, 1
	s_sub_i32 s38, s101, s17
	s_cmp_ge_u32 s101, s17
	s_cselect_b32 s25, s39, s25
	s_cselect_b32 s101, s38, s101
	s_add_i32 s38, s25, 1
	s_cmp_ge_u32 s101, s17
	s_cselect_b32 s101, s38, s25
	s_xor_b32 s101, s101, s24
	s_sub_i32 s24, s101, s24
	s_mul_i32 s101, s24, s15
	s_sub_i32 s100, s100, s101
	s_add_i32 s38, s14, s100
.Lgu_idx_skip:
	s_ashr_i32 s39, s38, 31
	s_lshl_b64 s[100:101], s[38:39], 19
	s_add_u32 s40, s54, s100
	s_addc_u32 s41, s55, s101
	s_and_b64 s[100:101], s[36:37], exec
	s_cselect_b32 s17, s41, s99
	s_cselect_b32 s39, s40, s98
	s_ashr_i32 s25, s24, 31
	s_lshl_b64 s[100:101], s[24:25], 19
	s_add_u32 s42, s26, s100
	s_addc_u32 s43, s27, s101
	s_and_b64 s[100:101], s[36:37], exec
	s_cselect_b32 s25, s43, s49
	s_cselect_b32 s59, s42, s48
	s_cmp_eq_u32 s57, 1
	s_cbranch_scc1 .Lgu_s2_first
	s_waitcnt vmcnt(14)
	s_branch .Lgu_s2_join
